# combination on top of global-word barrier polling: P10 epilogue packed-f32 rewrite, P4 DPP-fused prefix, P8 int8 packing via magic-number rounding + v_perm, barrier tail wait removed, P2 seam store-dr
# speedup vs baseline: 1.0023x; 1.0023x over previous
.LBB0_325:
	s_and_b64 vcc, exec, s[6:7]
	s_cbranch_vccnz .LBB0_327
	s_barrier

.LBB0_355:
	s_andn2_b64 vcc, exec, s[36:37]
	s_cbranch_vccnz .LBB0_357
	s_barrier

.LBB0_633:
	s_mov_b32 s98, 0x4b400000
	s_mov_b32 s100, 0xc0c0400
	s_mov_b32 s101, 0x5040100
	s_waitcnt lgkmcnt(1)
	v_lshlrev_b64 v[40:41], 2, v[188:189]
	v_lshl_add_u64 v[86:87], s[38:39], 0, v[40:41]
	global_load_dword v91, v[86:87], off sc1
	global_load_dword v90, v[86:87], off offset:64 sc1
	global_load_dword v85, v[86:87], off offset:128 sc1
	global_load_dword v84, v[86:87], off offset:192 sc1
	global_load_dword v83, v[86:87], off offset:512 sc1
	global_load_dword v82, v[86:87], off offset:576 sc1
	s_waitcnt lgkmcnt(0)
	global_load_dword v81, v[86:87], off offset:640 sc1
	global_load_dword v80, v[86:87], off offset:704 sc1
	s_lshl_b64 s[2:3], s[64:65], 2
	s_add_u32 s2, s91, s2
	s_addc_u32 s3, s92, s3
	v_lshl_add_u64 v[40:41], s[40:41], 0, v[40:41]
	global_load_dword v88, v161, s[2:3]
	global_load_dword v89, v[40:41], off sc1
	global_load_dword v236, v[40:41], off offset:64 sc1
	global_load_dword v237, v[40:41], off offset:128 sc1
	global_load_dword v238, v[40:41], off offset:192 sc1
	global_load_dword v239, v[40:41], off offset:512 sc1
	global_load_dword v240, v[40:41], off offset:576 sc1
	global_load_dword v241, v[40:41], off offset:640 sc1
	global_load_dword v242, v[40:41], off offset:704 sc1
	s_waitcnt vmcnt(15)
	v_pk_fma_f32 v[86:87], v[90:91], s[54:55], v[172:173] op_sel_hi:[1,0,0]
	s_nop 0
	v_mul_f32_e32 v90, 0x4b800000, v87
	v_cmp_gt_f32_e64 s[2:3], s86, v87
	s_nop 1
	v_cndmask_b32_e64 v87, v87, v90, s[2:3]
	v_rsq_f32_e32 v87, v87
	v_or_b32_e32 v90, s14, v230
	v_cmp_eq_u32_e32 vcc, 0, v90
	v_cmp_gt_f32_e64 s[14:15], s86, v86
	v_mul_f32_e32 v90, 0x45800000, v87
	v_cndmask_b32_e64 v202, v87, v90, s[2:3]
	s_waitcnt vmcnt(0)
	v_mul_f32_e32 v87, v202, v89
	v_sub_f32_e32 v89, 1.0, v202
	v_max_f32_e32 v89, 0, v89
	v_fmac_f32_e32 v87, v88, v89
	s_and_saveexec_b64 s[2:3], vcc
	s_cbranch_execz .LBB0_635
	v_mul_f32_e32 v89, 0x3c010204, v87
	v_lshl_add_u64 v[90:91], v[188:189], 2, s[42:43]
	global_store_dword v[90:91], v89, off

.LBB0_649:
	s_or_b64 exec, exec, s[2:3]
	v_div_scale_f32 v42, s[2:3], v41, v41, s87
	v_rcp_f32_e32 v43, v42
	v_div_scale_f32 v82, vcc, s87, v41, s87
	v_fma_f32 v83, -v42, v43, 1.0
	v_fmac_f32_e32 v43, v83, v43
	v_mul_f32_e32 v83, v82, v43
	v_fma_f32 v88, -v42, v83, v82
	v_fmac_f32_e32 v83, v88, v43
	v_fma_f32 v42, -v42, v83, v82
	v_div_fmas_f32 v42, v42, v43, v83
	v_div_scale_f32 v43, s[2:3], v81, v81, s87
	v_rcp_f32_e32 v82, v43
	v_div_fixup_f32 v42, v42, v41, s87
	v_cmp_lt_f32_e32 vcc, 0, v41
	v_fma_f32 v41, -v43, v82, 1.0
	s_nop 0
	v_cndmask_b32_e32 v42, 0, v42, vcc
	v_fmac_f32_e32 v82, v41, v82
	v_div_scale_f32 v41, vcc, s87, v81, s87
	v_mul_f32_e32 v83, v41, v82
	v_fma_f32 v88, -v43, v83, v41
	v_fmac_f32_e32 v83, v88, v82
	v_fma_f32 v41, -v43, v83, v41
	v_div_scale_f32 v43, s[2:3], v94, v94, s87
	v_div_fmas_f32 v41, v41, v82, v83
	v_rcp_f32_e32 v83, v43
	v_div_fixup_f32 v41, v41, v81, s87
	v_cmp_lt_f32_e32 vcc, 0, v81
	s_nop 1
	v_cndmask_b32_e32 v82, 0, v41, vcc
	v_fma_f32 v41, -v43, v83, 1.0
	v_fmac_f32_e32 v83, v41, v83
	v_div_scale_f32 v41, vcc, s87, v94, s87
	v_mul_f32_e32 v81, v41, v83
	v_fma_f32 v88, -v43, v81, v41
	v_fmac_f32_e32 v81, v88, v83
	v_fma_f32 v41, -v43, v81, v41
	v_div_scale_f32 v43, s[2:3], v93, v93, s87
	v_div_fmas_f32 v41, v41, v83, v81
	v_rcp_f32_e32 v81, v43
	v_div_fixup_f32 v41, v41, v94, s87
	v_cmp_lt_f32_e32 vcc, 0, v94
	s_nop 1
	v_cndmask_b32_e32 v88, 0, v41, vcc
	v_fma_f32 v41, -v43, v81, 1.0
	v_fmac_f32_e32 v81, v41, v81
	v_div_scale_f32 v41, vcc, s87, v93, s87
	v_mul_f32_e32 v83, v41, v81
	v_fma_f32 v94, -v43, v83, v41
	v_fmac_f32_e32 v83, v94, v81
	v_fma_f32 v41, -v43, v83, v41
	v_div_scale_f32 v43, s[2:3], v91, v91, s87
	v_div_fmas_f32 v41, v41, v81, v83
	v_rcp_f32_e32 v81, v43
	v_div_fixup_f32 v41, v41, v93, s87
	v_cmp_lt_f32_e32 vcc, 0, v93
	s_nop 1
	v_cndmask_b32_e32 v94, 0, v41, vcc
	v_fma_f32 v41, -v43, v81, 1.0
	v_fmac_f32_e32 v81, v41, v81
	v_div_scale_f32 v41, vcc, s87, v91, s87
	v_mul_f32_e32 v83, v41, v81
	v_fma_f32 v93, -v43, v83, v41
	v_fmac_f32_e32 v83, v93, v81
	v_fma_f32 v41, -v43, v83, v41
	v_div_scale_f32 v43, s[2:3], v85, v85, s87
	v_div_fmas_f32 v41, v41, v81, v83
	v_rcp_f32_e32 v81, v43
	v_div_fixup_f32 v41, v41, v91, s87
	v_cmp_lt_f32_e32 vcc, 0, v91
	s_nop 1
	v_cndmask_b32_e32 v198, 0, v41, vcc
	v_fma_f32 v41, -v43, v81, 1.0
	v_fmac_f32_e32 v81, v41, v81
	v_div_scale_f32 v41, vcc, s87, v85, s87
	v_mul_f32_e32 v83, v41, v81
	v_fma_f32 v91, -v43, v83, v41
	v_fmac_f32_e32 v83, v91, v81
	v_fma_f32 v41, -v43, v83, v41
	v_div_scale_f32 v43, s[2:3], v89, v89, s87
	v_div_fmas_f32 v41, v41, v81, v83
	v_rcp_f32_e32 v81, v43
	v_div_fixup_f32 v41, v41, v85, s87
	v_cmp_lt_f32_e32 vcc, 0, v85
	s_nop 1
	v_cndmask_b32_e32 v204, 0, v41, vcc
	v_fma_f32 v41, -v43, v81, 1.0
	v_fmac_f32_e32 v81, v41, v81
	v_div_scale_f32 v41, vcc, s87, v89, s87
	v_mul_f32_e32 v83, v41, v81
	v_fma_f32 v85, -v43, v83, v41
	v_fmac_f32_e32 v83, v85, v81
	v_fma_f32 v41, -v43, v83, v41
	v_div_scale_f32 v43, s[2:3], v87, v87, s87
	v_div_fmas_f32 v41, v41, v81, v83
	v_rcp_f32_e32 v81, v43
	v_div_fixup_f32 v41, v41, v89, s87
	v_cmp_lt_f32_e32 vcc, 0, v89
	s_nop 1
	v_cndmask_b32_e32 v206, 0, v41, vcc
	v_fma_f32 v41, -v43, v81, 1.0
	v_fmac_f32_e32 v81, v41, v81
	v_div_scale_f32 v41, vcc, s87, v87, s87
	v_mul_f32_e32 v83, v41, v81
	v_fma_f32 v85, -v43, v83, v41
	v_fmac_f32_e32 v83, v85, v81
	v_fma_f32 v41, -v43, v83, v41
	v_div_fmas_f32 v41, v41, v81, v83
	v_div_fixup_f32 v41, v41, v87, s87
	v_cmp_lt_f32_e32 vcc, 0, v87
	s_nop 1
	v_cndmask_b32_e32 v208, 0, v41, vcc
	v_lshl_add_u32 v41, v188, 10, v186
	v_lshlrev_b32_e32 v43, 1, v41
	v_and_b32_e32 v43, 0x7ffffef0, v43
	v_cvt_pk_bf16_f32 v186, v192, v193
	v_cvt_pk_bf16_f32 v187, v190, v191
	v_cvt_pk_bf16_f32 v188, v152, v153
	v_cvt_pk_bf16_f32 v189, v154, v155
	global_store_dwordx4 v43, v[186:189], s[36:37]
	v_pk_mul_f32 v[152:153], v[152:153], v[202:203] op_sel_hi:[1,0]
	v_pk_mul_f32 v[154:155], v[154:155], v[202:203] op_sel_hi:[1,0]
	v_pk_mul_f32 v[188:189], v[192:193], v[202:203] op_sel_hi:[1,0]
	v_pk_mul_f32 v[186:187], v[190:191], v[202:203] op_sel_hi:[1,0]
	v_pk_fma_f32 v[188:189], v[184:185], v[188:189], v[12:13]
	v_pk_fma_f32 v[186:187], v[182:183], v[186:187], v[14:15]
	v_pk_mul_f32 v[188:189], v[188:189], v[208:209] op_sel_hi:[1,0]
	v_pk_fma_f32 v[152:153], v[180:181], v[152:153], v[4:5]
	v_pk_mul_f32 v[186:187], v[186:187], v[208:209] op_sel_hi:[1,0]
	v_pk_fma_f32 v[154:155], v[178:179], v[154:155], v[6:7]
	v_pk_mul_f32 v[152:153], v[152:153], v[208:209] op_sel_hi:[1,0]
	v_pk_add_f32 v[188:189], v[188:189], s[98:99] op_sel_hi:[1,0]
	v_pk_add_f32 v[186:187], v[186:187], s[98:99] op_sel_hi:[1,0]
	v_perm_b32 v83, v189, v188, s100
	v_perm_b32 v85, v187, v186, s100
	v_pk_mul_f32 v[154:155], v[154:155], v[208:209] op_sel_hi:[1,0]
	v_pk_add_f32 v[152:153], v[152:153], s[98:99] op_sel_hi:[1,0]
	v_pk_add_f32 v[154:155], v[154:155], s[98:99] op_sel_hi:[1,0]
	v_perm_b32 v91, v153, v152, s100
	v_perm_b32 v93, v155, v154, s100
	v_perm_b32 v152, v85, v83, s101
	v_and_b32_e32 v81, 0x3fffff78, v41
	v_perm_b32 v153, v93, v91, s101
	global_store_dwordx2 v81, v[152:153], s[28:29]
	v_cvt_pk_bf16_f32 v152, v148, v149
	v_pk_mul_f32 v[148:149], v[148:149], v[202:203] op_sel_hi:[1,0]
	v_cvt_pk_bf16_f32 v153, v150, v151
	v_pk_mul_f32 v[150:151], v[150:151], v[202:203] op_sel_hi:[1,0]
	v_pk_fma_f32 v[148:149], v[158:159], v[148:149], v[8:9]
	v_cvt_pk_bf16_f32 v154, v144, v145
	v_pk_fma_f32 v[150:151], v[156:157], v[150:151], v[10:11]
	v_pk_mul_f32 v[144:145], v[144:145], v[202:203] op_sel_hi:[1,0]
	v_pk_mul_f32 v[148:149], v[148:149], v[208:209] op_sel_hi:[1,0]
	v_cvt_pk_bf16_f32 v155, v146, v147
	v_pk_mul_f32 v[146:147], v[146:147], v[202:203] op_sel_hi:[1,0]
	v_pk_fma_f32 v[144:145], v[176:177], v[144:145], v[0:1]
	v_pk_mul_f32 v[150:151], v[150:151], v[208:209] op_sel_hi:[1,0]
	global_store_dwordx4 v43, v[152:155], s[36:37] offset:256
	v_pk_fma_f32 v[146:147], v[174:175], v[146:147], v[2:3]
	v_pk_mul_f32 v[144:145], v[144:145], v[208:209] op_sel_hi:[1,0]
	v_pk_add_f32 v[148:149], v[148:149], s[98:99] op_sel_hi:[1,0]
	v_pk_add_f32 v[150:151], v[150:151], s[98:99] op_sel_hi:[1,0]
	v_perm_b32 v43, v149, v148, s100
	v_perm_b32 v83, v151, v150, s100
	v_pk_mul_f32 v[146:147], v[146:147], v[208:209] op_sel_hi:[1,0]
	v_pk_add_f32 v[144:145], v[144:145], s[98:99] op_sel_hi:[1,0]
	v_pk_add_f32 v[146:147], v[146:147], s[98:99] op_sel_hi:[1,0]
	v_perm_b32 v89, v145, v144, s100
	v_perm_b32 v91, v147, v146, s100
	v_perm_b32 v144, v83, v43, s101
	v_perm_b32 v145, v91, v89, s101
	global_store_dwordx2 v81, v[144:145], s[28:29] offset:128
	v_cvt_pk_bf16_f32 v144, v140, v141
	v_pk_mul_f32 v[140:141], v[140:141], v[200:201] op_sel_hi:[1,0]
	v_cvt_pk_bf16_f32 v145, v142, v143
	v_pk_mul_f32 v[142:143], v[142:143], v[200:201] op_sel_hi:[1,0]
	v_pk_fma_f32 v[140:141], v[184:185], v[140:141], v[12:13]
	v_cvt_pk_bf16_f32 v146, v136, v137
	v_pk_fma_f32 v[142:143], v[182:183], v[142:143], v[14:15]
	v_pk_mul_f32 v[136:137], v[136:137], v[200:201] op_sel_hi:[1,0]
	v_pk_mul_f32 v[140:141], v[140:141], v[206:207] op_sel_hi:[1,0]
	v_cvt_pk_bf16_f32 v147, v138, v139
	v_pk_mul_f32 v[138:139], v[138:139], v[200:201] op_sel_hi:[1,0]
	v_pk_fma_f32 v[136:137], v[180:181], v[136:137], v[4:5]
	v_pk_mul_f32 v[142:143], v[142:143], v[206:207] op_sel_hi:[1,0]
	v_pk_fma_f32 v[138:139], v[178:179], v[138:139], v[6:7]
	v_pk_mul_f32 v[136:137], v[136:137], v[206:207] op_sel_hi:[1,0]
	v_pk_add_f32 v[140:141], v[140:141], s[98:99] op_sel_hi:[1,0]
	v_pk_add_f32 v[142:143], v[142:143], s[98:99] op_sel_hi:[1,0]
	v_perm_b32 v83, v141, v140, s100
	v_perm_b32 v85, v143, v142, s100
	v_pk_mul_f32 v[138:139], v[138:139], v[206:207] op_sel_hi:[1,0]
	v_pk_add_f32 v[136:137], v[136:137], s[98:99] op_sel_hi:[1,0]
	v_pk_add_f32 v[138:139], v[138:139], s[98:99] op_sel_hi:[1,0]
	v_perm_b32 v91, v137, v136, s100
	v_perm_b32 v93, v139, v138, s100
	v_add_u32_e32 v43, 0x4000, v41
	v_perm_b32 v136, v85, v83, s101
	v_lshlrev_b32_e32 v81, 1, v43
	v_and_b32_e32 v81, 0x7ffffef0, v81
	v_and_b32_e32 v43, 0x3fffff78, v43
	v_perm_b32 v137, v93, v91, s101
	global_store_dwordx4 v81, v[144:147], s[36:37]
	global_store_dwordx2 v43, v[136:137], s[28:29]
	v_cvt_pk_bf16_f32 v136, v132, v133
	v_pk_mul_f32 v[132:133], v[132:133], v[200:201] op_sel_hi:[1,0]
	v_cvt_pk_bf16_f32 v137, v134, v135
	v_pk_mul_f32 v[134:135], v[134:135], v[200:201] op_sel_hi:[1,0]
	v_pk_fma_f32 v[132:133], v[158:159], v[132:133], v[8:9]
	v_cvt_pk_bf16_f32 v138, v128, v129
	v_pk_fma_f32 v[134:135], v[156:157], v[134:135], v[10:11]
	v_pk_mul_f32 v[128:129], v[128:129], v[200:201] op_sel_hi:[1,0]
	v_pk_mul_f32 v[132:133], v[132:133], v[206:207] op_sel_hi:[1,0]
	v_cvt_pk_bf16_f32 v139, v130, v131
	v_pk_mul_f32 v[130:131], v[130:131], v[200:201] op_sel_hi:[1,0]
	v_pk_fma_f32 v[128:129], v[176:177], v[128:129], v[0:1]
	v_pk_mul_f32 v[134:135], v[134:135], v[206:207] op_sel_hi:[1,0]
	global_store_dwordx4 v81, v[136:139], s[36:37] offset:256
	v_pk_fma_f32 v[130:131], v[174:175], v[130:131], v[2:3]
	v_pk_mul_f32 v[128:129], v[128:129], v[206:207] op_sel_hi:[1,0]
	v_pk_add_f32 v[132:133], v[132:133], s[98:99] op_sel_hi:[1,0]
	v_pk_add_f32 v[134:135], v[134:135], s[98:99] op_sel_hi:[1,0]
	v_perm_b32 v81, v133, v132, s100
	v_perm_b32 v83, v135, v134, s100
	v_pk_mul_f32 v[130:131], v[130:131], v[206:207] op_sel_hi:[1,0]
	v_pk_add_f32 v[128:129], v[128:129], s[98:99] op_sel_hi:[1,0]
	v_pk_add_f32 v[130:131], v[130:131], s[98:99] op_sel_hi:[1,0]
	v_perm_b32 v89, v129, v128, s100
	v_perm_b32 v91, v131, v130, s100
	v_perm_b32 v128, v83, v81, s101
	v_perm_b32 v129, v91, v89, s101
	global_store_dwordx2 v43, v[128:129], s[28:29] offset:128
	v_cvt_pk_bf16_f32 v128, v124, v125
	v_pk_mul_f32 v[124:125], v[124:125], v[92:93] op_sel_hi:[1,0]
	v_cvt_pk_bf16_f32 v129, v126, v127
	v_pk_mul_f32 v[126:127], v[126:127], v[92:93] op_sel_hi:[1,0]
	v_pk_fma_f32 v[124:125], v[184:185], v[124:125], v[12:13]
	v_cvt_pk_bf16_f32 v130, v120, v121
	v_pk_fma_f32 v[126:127], v[182:183], v[126:127], v[14:15]
	v_pk_mul_f32 v[120:121], v[120:121], v[92:93] op_sel_hi:[1,0]
	v_pk_mul_f32 v[124:125], v[124:125], v[204:205] op_sel_hi:[1,0]
	v_cvt_pk_bf16_f32 v131, v122, v123
	v_pk_mul_f32 v[122:123], v[122:123], v[92:93] op_sel_hi:[1,0]
	v_pk_fma_f32 v[120:121], v[180:181], v[120:121], v[4:5]
	v_pk_mul_f32 v[126:127], v[126:127], v[204:205] op_sel_hi:[1,0]
	v_pk_fma_f32 v[122:123], v[178:179], v[122:123], v[6:7]
	v_pk_mul_f32 v[120:121], v[120:121], v[204:205] op_sel_hi:[1,0]
	v_pk_add_f32 v[124:125], v[124:125], s[98:99] op_sel_hi:[1,0]
	v_pk_add_f32 v[126:127], v[126:127], s[98:99] op_sel_hi:[1,0]
	v_perm_b32 v83, v125, v124, s100
	v_perm_b32 v85, v127, v126, s100
	v_pk_mul_f32 v[122:123], v[122:123], v[204:205] op_sel_hi:[1,0]
	v_pk_add_f32 v[120:121], v[120:121], s[98:99] op_sel_hi:[1,0]
	v_pk_add_f32 v[122:123], v[122:123], s[98:99] op_sel_hi:[1,0]
	v_perm_b32 v91, v121, v120, s100
	v_perm_b32 v93, v123, v122, s100
	v_add_u32_e32 v43, 0x8000, v41
	v_perm_b32 v120, v85, v83, s101
	v_lshlrev_b32_e32 v81, 1, v43
	v_and_b32_e32 v81, 0x7ffffef0, v81
	v_and_b32_e32 v43, 0x3fffff78, v43
	v_perm_b32 v121, v93, v91, s101
	global_store_dwordx4 v81, v[128:131], s[36:37]
	global_store_dwordx2 v43, v[120:121], s[28:29]
	v_cvt_pk_bf16_f32 v120, v116, v117
	v_pk_mul_f32 v[116:117], v[116:117], v[92:93] op_sel_hi:[1,0]
	v_cvt_pk_bf16_f32 v121, v118, v119
	v_pk_mul_f32 v[118:119], v[118:119], v[92:93] op_sel_hi:[1,0]
	v_pk_fma_f32 v[116:117], v[158:159], v[116:117], v[8:9]
	v_cvt_pk_bf16_f32 v122, v112, v113
	v_cvt_pk_bf16_f32 v123, v114, v115
	v_pk_fma_f32 v[118:119], v[156:157], v[118:119], v[10:11]
	v_pk_mul_f32 v[114:115], v[114:115], v[92:93] op_sel_hi:[1,0]
	v_pk_mul_f32 v[92:93], v[112:113], v[92:93] op_sel_hi:[1,0]
	v_pk_mul_f32 v[116:117], v[116:117], v[204:205] op_sel_hi:[1,0]
	v_pk_fma_f32 v[112:113], v[174:175], v[114:115], v[2:3]
	v_pk_fma_f32 v[92:93], v[176:177], v[92:93], v[0:1]
	v_pk_mul_f32 v[114:115], v[118:119], v[204:205] op_sel_hi:[1,0]
	global_store_dwordx4 v81, v[120:123], s[36:37] offset:256
	v_pk_mul_f32 v[112:113], v[112:113], v[204:205] op_sel_hi:[1,0]
	v_pk_mul_f32 v[92:93], v[92:93], v[204:205] op_sel_hi:[1,0]
	v_pk_add_f32 v[116:117], v[116:117], s[98:99] op_sel_hi:[1,0]
	v_pk_add_f32 v[114:115], v[114:115], s[98:99] op_sel_hi:[1,0]
	v_perm_b32 v81, v117, v116, s100
	v_perm_b32 v83, v115, v114, s100
	v_pk_add_f32 v[92:93], v[92:93], s[98:99] op_sel_hi:[1,0]
	v_pk_add_f32 v[112:113], v[112:113], s[98:99] op_sel_hi:[1,0]
	v_perm_b32 v89, v93, v92, s100
	v_perm_b32 v91, v113, v112, s100
	v_perm_b32 v92, v83, v81, s101
	v_perm_b32 v93, v91, v89, s101
	global_store_dwordx2 v43, v[92:93], s[28:29] offset:128
	v_cvt_pk_bf16_f32 v112, v108, v109
	v_pk_mul_f32 v[108:109], v[108:109], v[90:91] op_sel_hi:[1,0]
	v_cvt_pk_bf16_f32 v113, v110, v111
	v_cvt_pk_bf16_f32 v114, v104, v105
	v_pk_mul_f32 v[92:93], v[110:111], v[90:91] op_sel_hi:[1,0]
	v_pk_fma_f32 v[108:109], v[184:185], v[108:109], v[12:13]
	v_pk_mul_f32 v[104:105], v[104:105], v[90:91] op_sel_hi:[1,0]
	v_cvt_pk_bf16_f32 v115, v106, v107
	v_pk_fma_f32 v[92:93], v[182:183], v[92:93], v[14:15]
	v_pk_mul_f32 v[106:107], v[106:107], v[90:91] op_sel_hi:[1,0]
	v_pk_fma_f32 v[104:105], v[180:181], v[104:105], v[4:5]
	v_pk_mul_f32 v[108:109], v[108:109], v[198:199] op_sel_hi:[1,0]
	v_pk_fma_f32 v[106:107], v[178:179], v[106:107], v[6:7]
	v_pk_mul_f32 v[92:93], v[92:93], v[198:199] op_sel_hi:[1,0]
	v_pk_mul_f32 v[104:105], v[104:105], v[198:199] op_sel_hi:[1,0]
	v_pk_mul_f32 v[106:107], v[106:107], v[198:199] op_sel_hi:[1,0]
	v_pk_add_f32 v[108:109], v[108:109], s[98:99] op_sel_hi:[1,0]
	v_pk_add_f32 v[92:93], v[92:93], s[98:99] op_sel_hi:[1,0]
	v_perm_b32 v83, v109, v108, s100
	v_perm_b32 v85, v93, v92, s100
	v_pk_add_f32 v[104:105], v[104:105], s[98:99] op_sel_hi:[1,0]
	v_pk_add_f32 v[106:107], v[106:107], s[98:99] op_sel_hi:[1,0]
	v_perm_b32 v91, v105, v104, s100
	v_perm_b32 v93, v107, v106, s100
	v_add_u32_e32 v43, 0xc000, v41
	v_perm_b32 v92, v85, v83, s101
	v_lshlrev_b32_e32 v81, 1, v43
	v_and_b32_e32 v81, 0x7ffffef0, v81
	v_and_b32_e32 v43, 0x3fffff78, v43
	v_perm_b32 v93, v93, v91, s101
	global_store_dwordx4 v81, v[112:115], s[36:37]
	global_store_dwordx2 v43, v[92:93], s[28:29]
	v_cvt_pk_bf16_f32 v104, v100, v101
	v_pk_mul_f32 v[100:101], v[100:101], v[90:91] op_sel_hi:[1,0]
	v_cvt_pk_bf16_f32 v105, v102, v103
	v_cvt_pk_bf16_f32 v106, v96, v97
	v_cvt_pk_bf16_f32 v107, v98, v99
	v_pk_mul_f32 v[92:93], v[102:103], v[90:91] op_sel_hi:[1,0]
	v_pk_fma_f32 v[100:101], v[158:159], v[100:101], v[8:9]
	v_pk_mul_f32 v[98:99], v[98:99], v[90:91] op_sel_hi:[1,0]
	v_pk_mul_f32 v[90:91], v[96:97], v[90:91] op_sel_hi:[1,0]
	v_pk_fma_f32 v[92:93], v[156:157], v[92:93], v[10:11]
	v_pk_fma_f32 v[96:97], v[174:175], v[98:99], v[2:3]
	v_pk_fma_f32 v[90:91], v[176:177], v[90:91], v[0:1]
	v_pk_mul_f32 v[98:99], v[100:101], v[198:199] op_sel_hi:[1,0]
	v_pk_mul_f32 v[92:93], v[92:93], v[198:199] op_sel_hi:[1,0]
	v_pk_mul_f32 v[90:91], v[90:91], v[198:199] op_sel_hi:[1,0]
	global_store_dwordx4 v81, v[104:107], s[36:37] offset:256
	v_pk_mul_f32 v[96:97], v[96:97], v[198:199] op_sel_hi:[1,0]
	v_pk_add_f32 v[98:99], v[98:99], s[98:99] op_sel_hi:[1,0]
	v_pk_add_f32 v[92:93], v[92:93], s[98:99] op_sel_hi:[1,0]
	v_perm_b32 v81, v99, v98, s100
	v_perm_b32 v83, v93, v92, s100
	v_pk_add_f32 v[90:91], v[90:91], s[98:99] op_sel_hi:[1,0]
	v_pk_add_f32 v[96:97], v[96:97], s[98:99] op_sel_hi:[1,0]
	v_perm_b32 v89, v91, v90, s100
	v_perm_b32 v92, v97, v96, s100
	v_perm_b32 v90, v83, v81, s101
	v_perm_b32 v91, v92, v89, s101
	global_store_dwordx2 v43, v[90:91], s[28:29] offset:128
	v_cvt_pk_bf16_f32 v90, v76, v77
	v_cvt_pk_bf16_f32 v91, v78, v79
	v_cvt_pk_bf16_f32 v92, v72, v73
	v_pk_mul_f32 v[72:73], v[72:73], v[86:87] op_sel_hi:[1,0]
	v_cvt_pk_bf16_f32 v93, v74, v75
	v_pk_mul_f32 v[76:77], v[76:77], v[86:87] op_sel_hi:[1,0]
	v_pk_fma_f32 v[72:73], v[180:181], v[72:73], v[4:5]
	v_pk_mul_f32 v[74:75], v[74:75], v[86:87] op_sel_hi:[1,0]
	v_pk_mul_f32 v[72:73], v[72:73], v[94:95] op_sel_hi:[1,0]
	v_pk_mul_f32 v[78:79], v[78:79], v[86:87] op_sel_hi:[1,0]
	v_pk_fma_f32 v[76:77], v[184:185], v[76:77], v[12:13]
	v_pk_fma_f32 v[74:75], v[178:179], v[74:75], v[6:7]
	v_pk_fma_f32 v[78:79], v[182:183], v[78:79], v[14:15]
	v_pk_mul_f32 v[76:77], v[76:77], v[94:95] op_sel_hi:[1,0]
	v_pk_mul_f32 v[74:75], v[74:75], v[94:95] op_sel_hi:[1,0]
	v_pk_mul_f32 v[78:79], v[78:79], v[94:95] op_sel_hi:[1,0]
	v_pk_add_f32 v[76:77], v[76:77], s[98:99] op_sel_hi:[1,0]
	v_pk_add_f32 v[78:79], v[78:79], s[98:99] op_sel_hi:[1,0]
	v_perm_b32 v76, v77, v76, s100
	v_perm_b32 v77, v79, v78, s100
	v_pk_add_f32 v[72:73], v[72:73], s[98:99] op_sel_hi:[1,0]
	v_pk_add_f32 v[74:75], v[74:75], s[98:99] op_sel_hi:[1,0]
	v_perm_b32 v83, v73, v72, s100
	v_perm_b32 v73, v75, v74, s100
	v_add_u32_e32 v43, 0x20000, v41
	v_lshlrev_b32_e32 v81, 1, v43
	v_and_b32_e32 v81, 0x7ffffef0, v81
	v_and_b32_e32 v43, 0x3fffff78, v43
	v_perm_b32 v72, v77, v76, s101
	v_perm_b32 v73, v73, v83, s101
	global_store_dwordx4 v81, v[90:93], s[36:37]
	global_store_dwordx2 v43, v[72:73], s[28:29]
	v_cvt_pk_bf16_f32 v72, v68, v69
	v_cvt_pk_bf16_f32 v73, v70, v71
	v_cvt_pk_bf16_f32 v74, v64, v65
	v_pk_mul_f32 v[64:65], v[64:65], v[86:87] op_sel_hi:[1,0]
	v_cvt_pk_bf16_f32 v75, v66, v67
	v_pk_mul_f32 v[68:69], v[68:69], v[86:87] op_sel_hi:[1,0]
	v_pk_fma_f32 v[64:65], v[176:177], v[64:65], v[0:1]
	v_pk_mul_f32 v[66:67], v[66:67], v[86:87] op_sel_hi:[1,0]
	v_pk_mul_f32 v[64:65], v[64:65], v[94:95] op_sel_hi:[1,0]
	v_pk_mul_f32 v[70:71], v[70:71], v[86:87] op_sel_hi:[1,0]
	v_pk_fma_f32 v[68:69], v[158:159], v[68:69], v[8:9]
	v_pk_fma_f32 v[66:67], v[174:175], v[66:67], v[2:3]
	global_store_dwordx4 v81, v[72:75], s[36:37] offset:256
	v_pk_fma_f32 v[70:71], v[156:157], v[70:71], v[10:11]
	v_pk_mul_f32 v[68:69], v[68:69], v[94:95] op_sel_hi:[1,0]
	v_pk_mul_f32 v[66:67], v[66:67], v[94:95] op_sel_hi:[1,0]
	v_pk_mul_f32 v[70:71], v[70:71], v[94:95] op_sel_hi:[1,0]
	v_pk_add_f32 v[68:69], v[68:69], s[98:99] op_sel_hi:[1,0]
	v_pk_add_f32 v[70:71], v[70:71], s[98:99] op_sel_hi:[1,0]
	v_perm_b32 v68, v69, v68, s100
	v_perm_b32 v69, v71, v70, s100
	v_pk_add_f32 v[64:65], v[64:65], s[98:99] op_sel_hi:[1,0]
	v_pk_add_f32 v[66:67], v[66:67], s[98:99] op_sel_hi:[1,0]
	v_perm_b32 v72, v65, v64, s100
	v_perm_b32 v65, v67, v66, s100
	v_perm_b32 v64, v69, v68, s101
	v_perm_b32 v65, v65, v72, s101
	global_store_dwordx2 v43, v[64:65], s[28:29] offset:128
	v_add_u32_e32 v43, 0x24000, v41
	v_lshlrev_b32_e32 v64, 1, v43
	v_and_b32_e32 v68, 0x7ffffef0, v64
	v_cvt_pk_bf16_f32 v64, v60, v61
	v_cvt_pk_bf16_f32 v65, v62, v63
	v_cvt_pk_bf16_f32 v66, v56, v57
	v_pk_mul_f32 v[56:57], v[56:57], v[84:85] op_sel_hi:[1,0]
	v_cvt_pk_bf16_f32 v67, v58, v59
	v_pk_mul_f32 v[60:61], v[60:61], v[84:85] op_sel_hi:[1,0]
	v_pk_fma_f32 v[56:57], v[180:181], v[56:57], v[4:5]
	v_pk_mul_f32 v[58:59], v[58:59], v[84:85] op_sel_hi:[1,0]
	v_pk_mul_f32 v[56:57], v[56:57], v[88:89] op_sel_hi:[1,0]
	v_pk_mul_f32 v[62:63], v[62:63], v[84:85] op_sel_hi:[1,0]
	v_pk_fma_f32 v[60:61], v[184:185], v[60:61], v[12:13]
	v_pk_fma_f32 v[58:59], v[178:179], v[58:59], v[6:7]
	global_store_dwordx4 v68, v[64:67], s[36:37]
	v_pk_fma_f32 v[62:63], v[182:183], v[62:63], v[14:15]
	v_pk_mul_f32 v[60:61], v[60:61], v[88:89] op_sel_hi:[1,0]
	v_pk_mul_f32 v[58:59], v[58:59], v[88:89] op_sel_hi:[1,0]
	v_pk_mul_f32 v[62:63], v[62:63], v[88:89] op_sel_hi:[1,0]
	v_pk_add_f32 v[60:61], v[60:61], s[98:99] op_sel_hi:[1,0]
	v_pk_add_f32 v[62:63], v[62:63], s[98:99] op_sel_hi:[1,0]
	v_perm_b32 v60, v61, v60, s100
	v_perm_b32 v61, v63, v62, s100
	v_pk_add_f32 v[56:57], v[56:57], s[98:99] op_sel_hi:[1,0]
	v_pk_add_f32 v[58:59], v[58:59], s[98:99] op_sel_hi:[1,0]
	v_perm_b32 v64, v57, v56, s100
	v_perm_b32 v57, v59, v58, s100
	v_and_b32_e32 v43, 0x3fffff78, v43
	v_perm_b32 v56, v61, v60, s101
	v_perm_b32 v57, v57, v64, s101
	global_store_dwordx2 v43, v[56:57], s[28:29]
	v_cvt_pk_bf16_f32 v56, v52, v53
	v_cvt_pk_bf16_f32 v57, v54, v55
	v_cvt_pk_bf16_f32 v58, v48, v49
	v_pk_mul_f32 v[48:49], v[48:49], v[84:85] op_sel_hi:[1,0]
	v_cvt_pk_bf16_f32 v59, v50, v51
	v_pk_mul_f32 v[52:53], v[52:53], v[84:85] op_sel_hi:[1,0]
	v_pk_fma_f32 v[48:49], v[176:177], v[48:49], v[0:1]
	v_pk_mul_f32 v[50:51], v[50:51], v[84:85] op_sel_hi:[1,0]
	v_pk_mul_f32 v[48:49], v[48:49], v[88:89] op_sel_hi:[1,0]
	v_pk_mul_f32 v[54:55], v[54:55], v[84:85] op_sel_hi:[1,0]
	v_pk_fma_f32 v[52:53], v[158:159], v[52:53], v[8:9]
	v_pk_fma_f32 v[50:51], v[174:175], v[50:51], v[2:3]
	global_store_dwordx4 v68, v[56:59], s[36:37] offset:256
	v_pk_fma_f32 v[54:55], v[156:157], v[54:55], v[10:11]
	v_pk_mul_f32 v[52:53], v[52:53], v[88:89] op_sel_hi:[1,0]
	v_pk_mul_f32 v[50:51], v[50:51], v[88:89] op_sel_hi:[1,0]
	v_pk_mul_f32 v[54:55], v[54:55], v[88:89] op_sel_hi:[1,0]
	v_pk_add_f32 v[52:53], v[52:53], s[98:99] op_sel_hi:[1,0]
	v_pk_add_f32 v[54:55], v[54:55], s[98:99] op_sel_hi:[1,0]
	v_perm_b32 v52, v53, v52, s100
	v_perm_b32 v53, v55, v54, s100
	v_pk_add_f32 v[48:49], v[48:49], s[98:99] op_sel_hi:[1,0]
	v_pk_add_f32 v[50:51], v[50:51], s[98:99] op_sel_hi:[1,0]
	v_perm_b32 v56, v49, v48, s100
	v_perm_b32 v49, v51, v50, s100
	v_perm_b32 v48, v53, v52, s101
	v_perm_b32 v49, v49, v56, s101
	global_store_dwordx2 v43, v[48:49], s[28:29] offset:128
	v_add_u32_e32 v43, 0x28000, v41
	v_lshlrev_b32_e32 v48, 1, v43
	v_and_b32_e32 v52, 0x7ffffef0, v48
	v_cvt_pk_bf16_f32 v48, v44, v45
	v_pk_mul_f32 v[44:45], v[44:45], v[80:81] op_sel_hi:[1,0]
	v_cvt_pk_bf16_f32 v49, v46, v47
	v_cvt_pk_bf16_f32 v50, v196, v197
	v_cvt_pk_bf16_f32 v51, v194, v195
	v_pk_mul_f32 v[46:47], v[46:47], v[80:81] op_sel_hi:[1,0]
	v_pk_fma_f32 v[44:45], v[184:185], v[44:45], v[12:13]
	global_store_dwordx4 v52, v[48:51], s[36:37]
	v_pk_fma_f32 v[46:47], v[182:183], v[46:47], v[14:15]
	v_pk_mul_f32 v[44:45], v[44:45], v[82:83] op_sel_hi:[1,0]
	v_pk_mul_f32 v[50:51], v[196:197], v[80:81] op_sel_hi:[1,0]
	v_pk_mul_f32 v[48:49], v[194:195], v[80:81] op_sel_hi:[1,0]
	v_pk_fma_f32 v[50:51], v[180:181], v[50:51], v[4:5]
	v_pk_mul_f32 v[46:47], v[46:47], v[82:83] op_sel_hi:[1,0]
	v_pk_fma_f32 v[48:49], v[178:179], v[48:49], v[6:7]
	v_pk_mul_f32 v[50:51], v[50:51], v[82:83] op_sel_hi:[1,0]
	v_pk_add_f32 v[44:45], v[44:45], s[98:99] op_sel_hi:[1,0]
	v_pk_add_f32 v[46:47], v[46:47], s[98:99] op_sel_hi:[1,0]
	v_perm_b32 v44, v45, v44, s100
	v_perm_b32 v45, v47, v46, s100
	v_pk_mul_f32 v[48:49], v[48:49], v[82:83] op_sel_hi:[1,0]
	v_pk_add_f32 v[50:51], v[50:51], s[98:99] op_sel_hi:[1,0]
	v_pk_add_f32 v[48:49], v[48:49], s[98:99] op_sel_hi:[1,0]
	v_perm_b32 v50, v51, v50, s100
	v_perm_b32 v48, v49, v48, s100
	v_perm_b32 v44, v45, v44, s101
	v_and_b32_e32 v43, 0x3fffff78, v43
	v_perm_b32 v45, v48, v50, s101
	global_store_dwordx2 v43, v[44:45], s[28:29]
	v_cvt_pk_bf16_f32 v44, v36, v37
	v_cvt_pk_bf16_f32 v45, v38, v39
	v_cvt_pk_bf16_f32 v46, v32, v33
	v_pk_mul_f32 v[32:33], v[32:33], v[80:81] op_sel_hi:[1,0]
	v_cvt_pk_bf16_f32 v47, v34, v35
	v_pk_mul_f32 v[36:37], v[36:37], v[80:81] op_sel_hi:[1,0]
	v_pk_fma_f32 v[32:33], v[176:177], v[32:33], v[0:1]
	v_pk_mul_f32 v[34:35], v[34:35], v[80:81] op_sel_hi:[1,0]
	v_pk_mul_f32 v[32:33], v[32:33], v[82:83] op_sel_hi:[1,0]
	v_pk_mul_f32 v[38:39], v[38:39], v[80:81] op_sel_hi:[1,0]
	v_pk_fma_f32 v[36:37], v[158:159], v[36:37], v[8:9]
	v_pk_fma_f32 v[34:35], v[174:175], v[34:35], v[2:3]
	global_store_dwordx4 v52, v[44:47], s[36:37] offset:256
	v_pk_fma_f32 v[38:39], v[156:157], v[38:39], v[10:11]
	v_pk_mul_f32 v[36:37], v[36:37], v[82:83] op_sel_hi:[1,0]
	v_pk_mul_f32 v[34:35], v[34:35], v[82:83] op_sel_hi:[1,0]
	v_pk_mul_f32 v[38:39], v[38:39], v[82:83] op_sel_hi:[1,0]
	v_pk_add_f32 v[36:37], v[36:37], s[98:99] op_sel_hi:[1,0]
	v_pk_add_f32 v[38:39], v[38:39], s[98:99] op_sel_hi:[1,0]
	v_perm_b32 v36, v37, v36, s100
	v_perm_b32 v37, v39, v38, s100
	v_pk_add_f32 v[32:33], v[32:33], s[98:99] op_sel_hi:[1,0]
	v_pk_add_f32 v[34:35], v[34:35], s[98:99] op_sel_hi:[1,0]
	v_perm_b32 v44, v33, v32, s100
	v_perm_b32 v33, v35, v34, s100
	v_perm_b32 v32, v37, v36, s101
	v_perm_b32 v33, v33, v44, s101
	global_store_dwordx2 v43, v[32:33], s[28:29] offset:128
	v_add_u32_e32 v32, 0x2c000, v41
	v_lshlrev_b32_e32 v33, 1, v32
	v_and_b32_e32 v36, 0x7ffffef0, v33
	v_and_b32_e32 v37, 0x3fffff78, v32
	v_cvt_pk_bf16_f32 v32, v28, v29
	v_cvt_pk_bf16_f32 v33, v30, v31
	v_cvt_pk_bf16_f32 v34, v24, v25
	v_pk_mul_f32 v[24:25], v[24:25], v[40:41] op_sel_hi:[1,0]
	v_cvt_pk_bf16_f32 v35, v26, v27
	v_pk_mul_f32 v[28:29], v[28:29], v[40:41] op_sel_hi:[1,0]
	v_pk_fma_f32 v[4:5], v[180:181], v[24:25], v[4:5]
	v_pk_mul_f32 v[26:27], v[26:27], v[40:41] op_sel_hi:[1,0]
	v_pk_mul_f32 v[4:5], v[4:5], v[42:43] op_sel_hi:[1,0]
	v_pk_mul_f32 v[30:31], v[30:31], v[40:41] op_sel_hi:[1,0]
	v_pk_fma_f32 v[12:13], v[184:185], v[28:29], v[12:13]
	v_pk_fma_f32 v[6:7], v[178:179], v[26:27], v[6:7]
	v_pk_fma_f32 v[14:15], v[182:183], v[30:31], v[14:15]
	v_pk_mul_f32 v[12:13], v[12:13], v[42:43] op_sel_hi:[1,0]
	v_pk_mul_f32 v[6:7], v[6:7], v[42:43] op_sel_hi:[1,0]
	v_pk_mul_f32 v[14:15], v[14:15], v[42:43] op_sel_hi:[1,0]
	v_pk_add_f32 v[12:13], v[12:13], s[98:99] op_sel_hi:[1,0]
	v_pk_add_f32 v[14:15], v[14:15], s[98:99] op_sel_hi:[1,0]
	v_perm_b32 v12, v13, v12, s100
	v_perm_b32 v13, v15, v14, s100
	v_pk_add_f32 v[4:5], v[4:5], s[98:99] op_sel_hi:[1,0]
	v_pk_add_f32 v[6:7], v[6:7], s[98:99] op_sel_hi:[1,0]
	v_perm_b32 v24, v5, v4, s100
	v_perm_b32 v5, v7, v6, s100
	v_perm_b32 v4, v13, v12, s101
	v_perm_b32 v5, v5, v24, s101
	global_store_dwordx4 v36, v[32:35], s[36:37]
	global_store_dwordx2 v37, v[4:5], s[28:29]
	v_cvt_pk_bf16_f32 v4, v20, v21
	v_cvt_pk_bf16_f32 v5, v22, v23
	v_cvt_pk_bf16_f32 v6, v16, v17
	v_cvt_pk_bf16_f32 v7, v18, v19
	global_store_dwordx4 v36, v[4:7], s[36:37] offset:256
	s_andn2_b64 vcc, exec, s[34:35]
	s_nop 0
	v_pk_mul_f32 v[4:5], v[22:23], v[40:41] op_sel_hi:[1,0]
	v_pk_mul_f32 v[6:7], v[20:21], v[40:41] op_sel_hi:[1,0]
	v_pk_fma_f32 v[4:5], v[156:157], v[4:5], v[10:11]
	v_pk_mul_f32 v[10:11], v[16:17], v[40:41] op_sel_hi:[1,0]
	v_pk_fma_f32 v[6:7], v[158:159], v[6:7], v[8:9]
	v_pk_fma_f32 v[0:1], v[176:177], v[10:11], v[0:1]
	v_pk_mul_f32 v[8:9], v[18:19], v[40:41] op_sel_hi:[1,0]
	v_pk_mul_f32 v[0:1], v[0:1], v[42:43] op_sel_hi:[1,0]
	v_pk_fma_f32 v[2:3], v[174:175], v[8:9], v[2:3]
	v_pk_mul_f32 v[6:7], v[6:7], v[42:43] op_sel_hi:[1,0]
	v_pk_mul_f32 v[2:3], v[2:3], v[42:43] op_sel_hi:[1,0]
	v_pk_mul_f32 v[4:5], v[4:5], v[42:43] op_sel_hi:[1,0]
	v_pk_add_f32 v[6:7], v[6:7], s[98:99] op_sel_hi:[1,0]
	v_pk_add_f32 v[4:5], v[4:5], s[98:99] op_sel_hi:[1,0]
	v_perm_b32 v6, v7, v6, s100
	v_perm_b32 v4, v5, v4, s100
	v_pk_add_f32 v[0:1], v[0:1], s[98:99] op_sel_hi:[1,0]
	v_pk_add_f32 v[2:3], v[2:3], s[98:99] op_sel_hi:[1,0]
	v_perm_b32 v8, v1, v0, s100
	v_perm_b32 v1, v3, v2, s100
	v_perm_b32 v0, v4, v6, s101
	v_perm_b32 v1, v1, v8, s101
	global_store_dwordx2 v37, v[0:1], s[28:29] offset:128
	s_cbranch_vccnz .LBB0_596
	s_barrier
	s_branch .LBB0_596

.LBB0_720:
	s_andn2_b64 vcc, exec, s[10:11]
	v_mov_b32_e32 v254, 0xbfb8aa3b
	v_mov_b32_e32 v255, 1.0
	v_lshl_or_b32 v190, s57, 7, v171
	v_ashrrev_i32_e32 v191, 31, v190
	v_mov_b64_e32 v[192:193], s[24:25]
	v_lshlrev_b64 v[190:191], 1, v[190:191]
	v_pk_mul_f32 v[160:161], v[228:229], v[160:161]
	v_pk_mul_f32 v[100:101], v[236:237], v[100:101]
	v_pk_mul_f32 v[160:161], v[160:161], v[244:245] op_sel_hi:[1,0]
	v_pk_mul_f32 v[100:101], v[100:101], v[244:245] op_sel_hi:[1,0]
	v_pk_mul_f32 v[162:163], v[230:231], v[162:163]
	v_pk_mul_f32 v[120:121], v[238:239], v[120:121]
	v_pk_mul_f32 v[162:163], v[162:163], v[244:245] op_sel_hi:[1,0]
	v_pk_mul_f32 v[120:121], v[120:121], v[244:245] op_sel_hi:[1,0]
	v_pk_mul_f32 v[146:147], v[232:233], v[146:147]
	v_pk_mul_f32 v[98:99], v[240:241], v[98:99]
	v_pk_mul_f32 v[146:147], v[146:147], v[244:245] op_sel_hi:[1,0]
	v_pk_mul_f32 v[98:99], v[98:99], v[244:245] op_sel_hi:[1,0]
	v_pk_mul_f32 v[158:159], v[234:235], v[158:159]
	v_pk_mul_f32 v[116:117], v[242:243], v[116:117]
	v_pk_mul_f32 v[158:159], v[158:159], v[244:245] op_sel_hi:[1,0]
	v_pk_mul_f32 v[116:117], v[116:117], v[244:245] op_sel_hi:[1,0]
	v_pk_mul_f32 v[178:179], v[160:161], v[254:255] op_sel_hi:[1,0]
	v_pk_mul_f32 v[180:181], v[162:163], v[254:255] op_sel_hi:[1,0]
	v_pk_mul_f32 v[182:183], v[146:147], v[254:255] op_sel_hi:[1,0]
	v_pk_mul_f32 v[184:185], v[158:159], v[254:255] op_sel_hi:[1,0]
	v_exp_f32_e32 v178, v178
	v_exp_f32_e32 v179, v179
	v_exp_f32_e32 v180, v180
	v_exp_f32_e32 v181, v181
	v_exp_f32_e32 v182, v182
	v_exp_f32_e32 v183, v183
	v_exp_f32_e32 v184, v184
	v_exp_f32_e32 v185, v185
	v_add_u32_e32 v196, 0x0, v223
	v_mad_i64_i32 v[194:195], s[20:21], v196, s56, v[192:193]
	v_pk_add_f32 v[178:179], v[178:179], v[254:255] op_sel:[0,1] op_sel_hi:[1,1]
	v_pk_add_f32 v[180:181], v[180:181], v[254:255] op_sel:[0,1] op_sel_hi:[1,1]
	v_pk_add_f32 v[182:183], v[182:183], v[254:255] op_sel:[0,1] op_sel_hi:[1,1]
	v_pk_add_f32 v[184:185], v[184:185], v[254:255] op_sel:[0,1] op_sel_hi:[1,1]
	v_rcp_f32_e32 v178, v178
	v_rcp_f32_e32 v179, v179
	v_rcp_f32_e32 v180, v180
	v_rcp_f32_e32 v181, v181
	v_rcp_f32_e32 v182, v182
	v_rcp_f32_e32 v183, v183
	v_rcp_f32_e32 v184, v184
	v_rcp_f32_e32 v185, v185
	v_lshl_add_u64 v[194:195], v[194:195], 0, v[190:191]
	v_pk_mul_f32 v[178:179], v[160:161], v[178:179]
	v_pk_mul_f32 v[180:181], v[162:163], v[180:181]
	v_pk_mul_f32 v[182:183], v[146:147], v[182:183]
	v_pk_mul_f32 v[184:185], v[158:159], v[184:185]
	v_pk_mul_f32 v[178:179], v[100:101], v[178:179]
	v_pk_mul_f32 v[180:181], v[120:121], v[180:181]
	v_pk_mul_f32 v[182:183], v[98:99], v[182:183]
	v_pk_mul_f32 v[184:185], v[116:117], v[184:185]
	v_cvt_pk_bf16_f32 v186, v178, v179
	v_cvt_pk_bf16_f32 v187, v180, v181
	v_cvt_pk_bf16_f32 v188, v182, v183
	v_cvt_pk_bf16_f32 v189, v184, v185
	global_store_dwordx4 v[194:195], v[186:189], off
	v_pk_mul_f32 v[144:145], v[228:229], v[144:145]
	v_pk_mul_f32 v[96:97], v[236:237], v[96:97]
	v_pk_mul_f32 v[144:145], v[144:145], v[244:245] op_sel:[0,1] op_sel_hi:[1,1]
	v_pk_mul_f32 v[96:97], v[96:97], v[244:245] op_sel:[0,1] op_sel_hi:[1,1]
	v_pk_mul_f32 v[156:157], v[230:231], v[156:157]
	v_pk_mul_f32 v[114:115], v[238:239], v[114:115]
	v_pk_mul_f32 v[156:157], v[156:157], v[244:245] op_sel:[0,1] op_sel_hi:[1,1]
	v_pk_mul_f32 v[114:115], v[114:115], v[244:245] op_sel:[0,1] op_sel_hi:[1,1]
	v_pk_mul_f32 v[140:141], v[232:233], v[140:141]
	v_pk_mul_f32 v[94:95], v[240:241], v[94:95]
	v_pk_mul_f32 v[140:141], v[140:141], v[244:245] op_sel:[0,1] op_sel_hi:[1,1]
	v_pk_mul_f32 v[94:95], v[94:95], v[244:245] op_sel:[0,1] op_sel_hi:[1,1]
	v_pk_mul_f32 v[154:155], v[234:235], v[154:155]
	v_pk_mul_f32 v[112:113], v[242:243], v[112:113]
	v_pk_mul_f32 v[154:155], v[154:155], v[244:245] op_sel:[0,1] op_sel_hi:[1,1]
	v_pk_mul_f32 v[112:113], v[112:113], v[244:245] op_sel:[0,1] op_sel_hi:[1,1]
	v_pk_mul_f32 v[178:179], v[144:145], v[254:255] op_sel_hi:[1,0]
	v_pk_mul_f32 v[180:181], v[156:157], v[254:255] op_sel_hi:[1,0]
	v_pk_mul_f32 v[182:183], v[140:141], v[254:255] op_sel_hi:[1,0]
	v_pk_mul_f32 v[184:185], v[154:155], v[254:255] op_sel_hi:[1,0]
	v_exp_f32_e32 v178, v178
	v_exp_f32_e32 v179, v179
	v_exp_f32_e32 v180, v180
	v_exp_f32_e32 v181, v181
	v_exp_f32_e32 v182, v182
	v_exp_f32_e32 v183, v183
	v_exp_f32_e32 v184, v184
	v_exp_f32_e32 v185, v185
	v_add_u32_e32 v196, 0x10, v223
	v_mad_i64_i32 v[194:195], s[20:21], v196, s56, v[192:193]
	v_pk_add_f32 v[178:179], v[178:179], v[254:255] op_sel:[0,1] op_sel_hi:[1,1]
	v_pk_add_f32 v[180:181], v[180:181], v[254:255] op_sel:[0,1] op_sel_hi:[1,1]
	v_pk_add_f32 v[182:183], v[182:183], v[254:255] op_sel:[0,1] op_sel_hi:[1,1]
	v_pk_add_f32 v[184:185], v[184:185], v[254:255] op_sel:[0,1] op_sel_hi:[1,1]
	v_rcp_f32_e32 v178, v178
	v_rcp_f32_e32 v179, v179
	v_rcp_f32_e32 v180, v180
	v_rcp_f32_e32 v181, v181
	v_rcp_f32_e32 v182, v182
	v_rcp_f32_e32 v183, v183
	v_rcp_f32_e32 v184, v184
	v_rcp_f32_e32 v185, v185
	v_lshl_add_u64 v[194:195], v[194:195], 0, v[190:191]
	v_pk_mul_f32 v[178:179], v[144:145], v[178:179]
	v_pk_mul_f32 v[180:181], v[156:157], v[180:181]
	v_pk_mul_f32 v[182:183], v[140:141], v[182:183]
	v_pk_mul_f32 v[184:185], v[154:155], v[184:185]
	v_pk_mul_f32 v[178:179], v[96:97], v[178:179]
	v_pk_mul_f32 v[180:181], v[114:115], v[180:181]
	v_pk_mul_f32 v[182:183], v[94:95], v[182:183]
	v_pk_mul_f32 v[184:185], v[112:113], v[184:185]
	v_cvt_pk_bf16_f32 v198, v178, v179
	v_cvt_pk_bf16_f32 v199, v180, v181
	v_cvt_pk_bf16_f32 v200, v182, v183
	v_cvt_pk_bf16_f32 v201, v184, v185
	global_store_dwordx4 v[194:195], v[198:201], off
	v_pk_mul_f32 v[126:127], v[228:229], v[126:127]
	v_pk_mul_f32 v[92:93], v[236:237], v[92:93]
	v_pk_mul_f32 v[126:127], v[126:127], v[246:247] op_sel_hi:[1,0]
	v_pk_mul_f32 v[92:93], v[92:93], v[246:247] op_sel_hi:[1,0]
	v_pk_mul_f32 v[152:153], v[230:231], v[152:153]
	v_pk_mul_f32 v[110:111], v[238:239], v[110:111]
	v_pk_mul_f32 v[152:153], v[152:153], v[246:247] op_sel_hi:[1,0]
	v_pk_mul_f32 v[110:111], v[110:111], v[246:247] op_sel_hi:[1,0]
	v_pk_mul_f32 v[124:125], v[232:233], v[124:125]
	v_pk_mul_f32 v[90:91], v[240:241], v[90:91]
	v_pk_mul_f32 v[124:125], v[124:125], v[246:247] op_sel_hi:[1,0]
	v_pk_mul_f32 v[90:91], v[90:91], v[246:247] op_sel_hi:[1,0]
	v_pk_mul_f32 v[150:151], v[234:235], v[150:151]
	v_pk_mul_f32 v[108:109], v[242:243], v[108:109]
	v_pk_mul_f32 v[150:151], v[150:151], v[246:247] op_sel_hi:[1,0]
	v_pk_mul_f32 v[108:109], v[108:109], v[246:247] op_sel_hi:[1,0]
	v_pk_mul_f32 v[178:179], v[126:127], v[254:255] op_sel_hi:[1,0]
	v_pk_mul_f32 v[180:181], v[152:153], v[254:255] op_sel_hi:[1,0]
	v_pk_mul_f32 v[182:183], v[124:125], v[254:255] op_sel_hi:[1,0]
	v_pk_mul_f32 v[184:185], v[150:151], v[254:255] op_sel_hi:[1,0]
	v_exp_f32_e32 v178, v178
	v_exp_f32_e32 v179, v179
	v_exp_f32_e32 v180, v180
	v_exp_f32_e32 v181, v181
	v_exp_f32_e32 v182, v182
	v_exp_f32_e32 v183, v183
	v_exp_f32_e32 v184, v184
	v_exp_f32_e32 v185, v185
	v_add_u32_e32 v196, 0x20, v223
	v_mad_i64_i32 v[194:195], s[20:21], v196, s56, v[192:193]
	v_pk_add_f32 v[178:179], v[178:179], v[254:255] op_sel:[0,1] op_sel_hi:[1,1]
	v_pk_add_f32 v[180:181], v[180:181], v[254:255] op_sel:[0,1] op_sel_hi:[1,1]
	v_pk_add_f32 v[182:183], v[182:183], v[254:255] op_sel:[0,1] op_sel_hi:[1,1]
	v_pk_add_f32 v[184:185], v[184:185], v[254:255] op_sel:[0,1] op_sel_hi:[1,1]
	v_rcp_f32_e32 v178, v178
	v_rcp_f32_e32 v179, v179
	v_rcp_f32_e32 v180, v180
	v_rcp_f32_e32 v181, v181
	v_rcp_f32_e32 v182, v182
	v_rcp_f32_e32 v183, v183
	v_rcp_f32_e32 v184, v184
	v_rcp_f32_e32 v185, v185
	v_lshl_add_u64 v[194:195], v[194:195], 0, v[190:191]
	v_pk_mul_f32 v[178:179], v[126:127], v[178:179]
	v_pk_mul_f32 v[180:181], v[152:153], v[180:181]
	v_pk_mul_f32 v[182:183], v[124:125], v[182:183]
	v_pk_mul_f32 v[184:185], v[150:151], v[184:185]
	v_pk_mul_f32 v[178:179], v[92:93], v[178:179]
	v_pk_mul_f32 v[180:181], v[110:111], v[180:181]
	v_pk_mul_f32 v[182:183], v[90:91], v[182:183]
	v_pk_mul_f32 v[184:185], v[108:109], v[184:185]
	v_cvt_pk_bf16_f32 v186, v178, v179
	v_cvt_pk_bf16_f32 v187, v180, v181
	v_cvt_pk_bf16_f32 v188, v182, v183
	v_cvt_pk_bf16_f32 v189, v184, v185
	global_store_dwordx4 v[194:195], v[186:189], off
	v_pk_mul_f32 v[122:123], v[228:229], v[122:123]
	v_pk_mul_f32 v[88:89], v[236:237], v[88:89]
	v_pk_mul_f32 v[122:123], v[122:123], v[246:247] op_sel:[0,1] op_sel_hi:[1,1]
	v_pk_mul_f32 v[88:89], v[88:89], v[246:247] op_sel:[0,1] op_sel_hi:[1,1]
	v_pk_mul_f32 v[148:149], v[230:231], v[148:149]
	v_pk_mul_f32 v[106:107], v[238:239], v[106:107]
	v_pk_mul_f32 v[148:149], v[148:149], v[246:247] op_sel:[0,1] op_sel_hi:[1,1]
	v_pk_mul_f32 v[106:107], v[106:107], v[246:247] op_sel:[0,1] op_sel_hi:[1,1]
	v_pk_mul_f32 v[118:119], v[232:233], v[118:119]
	v_pk_mul_f32 v[86:87], v[240:241], v[86:87]
	v_pk_mul_f32 v[118:119], v[118:119], v[246:247] op_sel:[0,1] op_sel_hi:[1,1]
	v_pk_mul_f32 v[86:87], v[86:87], v[246:247] op_sel:[0,1] op_sel_hi:[1,1]
	v_pk_mul_f32 v[142:143], v[234:235], v[142:143]
	v_pk_mul_f32 v[104:105], v[242:243], v[104:105]
	v_pk_mul_f32 v[142:143], v[142:143], v[246:247] op_sel:[0,1] op_sel_hi:[1,1]
	v_pk_mul_f32 v[104:105], v[104:105], v[246:247] op_sel:[0,1] op_sel_hi:[1,1]
	v_pk_mul_f32 v[178:179], v[122:123], v[254:255] op_sel_hi:[1,0]
	v_pk_mul_f32 v[180:181], v[148:149], v[254:255] op_sel_hi:[1,0]
	v_pk_mul_f32 v[182:183], v[118:119], v[254:255] op_sel_hi:[1,0]
	v_pk_mul_f32 v[184:185], v[142:143], v[254:255] op_sel_hi:[1,0]
	v_exp_f32_e32 v178, v178
	v_exp_f32_e32 v179, v179
	v_exp_f32_e32 v180, v180
	v_exp_f32_e32 v181, v181
	v_exp_f32_e32 v182, v182
	v_exp_f32_e32 v183, v183
	v_exp_f32_e32 v184, v184
	v_exp_f32_e32 v185, v185
	v_add_u32_e32 v196, 0x30, v223
	v_mad_i64_i32 v[194:195], s[20:21], v196, s56, v[192:193]
	v_pk_add_f32 v[178:179], v[178:179], v[254:255] op_sel:[0,1] op_sel_hi:[1,1]
	v_pk_add_f32 v[180:181], v[180:181], v[254:255] op_sel:[0,1] op_sel_hi:[1,1]
	v_pk_add_f32 v[182:183], v[182:183], v[254:255] op_sel:[0,1] op_sel_hi:[1,1]
	v_pk_add_f32 v[184:185], v[184:185], v[254:255] op_sel:[0,1] op_sel_hi:[1,1]
	v_rcp_f32_e32 v178, v178
	v_rcp_f32_e32 v179, v179
	v_rcp_f32_e32 v180, v180
	v_rcp_f32_e32 v181, v181
	v_rcp_f32_e32 v182, v182
	v_rcp_f32_e32 v183, v183
	v_rcp_f32_e32 v184, v184
	v_rcp_f32_e32 v185, v185
	v_lshl_add_u64 v[194:195], v[194:195], 0, v[190:191]
	v_pk_mul_f32 v[178:179], v[122:123], v[178:179]
	v_pk_mul_f32 v[180:181], v[148:149], v[180:181]
	v_pk_mul_f32 v[182:183], v[118:119], v[182:183]
	v_pk_mul_f32 v[184:185], v[142:143], v[184:185]
	v_pk_mul_f32 v[178:179], v[88:89], v[178:179]
	v_pk_mul_f32 v[180:181], v[106:107], v[180:181]
	v_pk_mul_f32 v[182:183], v[86:87], v[182:183]
	v_pk_mul_f32 v[184:185], v[104:105], v[184:185]
	v_cvt_pk_bf16_f32 v198, v178, v179
	v_cvt_pk_bf16_f32 v199, v180, v181
	v_cvt_pk_bf16_f32 v200, v182, v183
	v_cvt_pk_bf16_f32 v201, v184, v185
	global_store_dwordx4 v[194:195], v[198:201], off
	v_pk_mul_f32 v[84:85], v[228:229], v[84:85]
	v_pk_mul_f32 v[38:39], v[236:237], v[38:39]
	v_pk_mul_f32 v[84:85], v[84:85], v[248:249] op_sel_hi:[1,0]
	v_pk_mul_f32 v[38:39], v[38:39], v[248:249] op_sel_hi:[1,0]
	v_pk_mul_f32 v[102:103], v[230:231], v[102:103]
	v_pk_mul_f32 v[66:67], v[238:239], v[66:67]
	v_pk_mul_f32 v[102:103], v[102:103], v[248:249] op_sel_hi:[1,0]
	v_pk_mul_f32 v[66:67], v[66:67], v[248:249] op_sel_hi:[1,0]
	v_pk_mul_f32 v[72:73], v[232:233], v[72:73]
	v_pk_mul_f32 v[36:37], v[240:241], v[36:37]
	v_pk_mul_f32 v[72:73], v[72:73], v[248:249] op_sel_hi:[1,0]
	v_pk_mul_f32 v[36:37], v[36:37], v[248:249] op_sel_hi:[1,0]
	v_pk_mul_f32 v[82:83], v[234:235], v[82:83]
	v_pk_mul_f32 v[64:65], v[242:243], v[64:65]
	v_pk_mul_f32 v[82:83], v[82:83], v[248:249] op_sel_hi:[1,0]
	v_pk_mul_f32 v[64:65], v[64:65], v[248:249] op_sel_hi:[1,0]
	v_pk_mul_f32 v[178:179], v[84:85], v[254:255] op_sel_hi:[1,0]
	v_pk_mul_f32 v[180:181], v[102:103], v[254:255] op_sel_hi:[1,0]
	v_pk_mul_f32 v[182:183], v[72:73], v[254:255] op_sel_hi:[1,0]
	v_pk_mul_f32 v[184:185], v[82:83], v[254:255] op_sel_hi:[1,0]
	v_exp_f32_e32 v178, v178
	v_exp_f32_e32 v179, v179
	v_exp_f32_e32 v180, v180
	v_exp_f32_e32 v181, v181
	v_exp_f32_e32 v182, v182
	v_exp_f32_e32 v183, v183
	v_exp_f32_e32 v184, v184
	v_exp_f32_e32 v185, v185
	v_add_u32_e32 v196, 0x80, v223
	v_mad_i64_i32 v[194:195], s[20:21], v196, s56, v[192:193]
	v_pk_add_f32 v[178:179], v[178:179], v[254:255] op_sel:[0,1] op_sel_hi:[1,1]
	v_pk_add_f32 v[180:181], v[180:181], v[254:255] op_sel:[0,1] op_sel_hi:[1,1]
	v_pk_add_f32 v[182:183], v[182:183], v[254:255] op_sel:[0,1] op_sel_hi:[1,1]
	v_pk_add_f32 v[184:185], v[184:185], v[254:255] op_sel:[0,1] op_sel_hi:[1,1]
	v_rcp_f32_e32 v178, v178
	v_rcp_f32_e32 v179, v179
	v_rcp_f32_e32 v180, v180
	v_rcp_f32_e32 v181, v181
	v_rcp_f32_e32 v182, v182
	v_rcp_f32_e32 v183, v183
	v_rcp_f32_e32 v184, v184
	v_rcp_f32_e32 v185, v185
	v_lshl_add_u64 v[194:195], v[194:195], 0, v[190:191]
	v_pk_mul_f32 v[178:179], v[84:85], v[178:179]
	v_pk_mul_f32 v[180:181], v[102:103], v[180:181]
	v_pk_mul_f32 v[182:183], v[72:73], v[182:183]
	v_pk_mul_f32 v[184:185], v[82:83], v[184:185]
	v_pk_mul_f32 v[178:179], v[38:39], v[178:179]
	v_pk_mul_f32 v[180:181], v[66:67], v[180:181]
	v_pk_mul_f32 v[182:183], v[36:37], v[182:183]
	v_pk_mul_f32 v[184:185], v[64:65], v[184:185]
	v_cvt_pk_bf16_f32 v186, v178, v179
	v_cvt_pk_bf16_f32 v187, v180, v181
	v_cvt_pk_bf16_f32 v188, v182, v183
	v_cvt_pk_bf16_f32 v189, v184, v185
	global_store_dwordx4 v[194:195], v[186:189], off
	v_pk_mul_f32 v[70:71], v[228:229], v[70:71]
	v_pk_mul_f32 v[34:35], v[236:237], v[34:35]
	v_pk_mul_f32 v[70:71], v[70:71], v[248:249] op_sel:[0,1] op_sel_hi:[1,1]
	v_pk_mul_f32 v[34:35], v[34:35], v[248:249] op_sel:[0,1] op_sel_hi:[1,1]
	v_pk_mul_f32 v[80:81], v[230:231], v[80:81]
	v_pk_mul_f32 v[62:63], v[238:239], v[62:63]
	v_pk_mul_f32 v[80:81], v[80:81], v[248:249] op_sel:[0,1] op_sel_hi:[1,1]
	v_pk_mul_f32 v[62:63], v[62:63], v[248:249] op_sel:[0,1] op_sel_hi:[1,1]
	v_pk_mul_f32 v[52:53], v[232:233], v[52:53]
	v_pk_mul_f32 v[32:33], v[240:241], v[32:33]
	v_pk_mul_f32 v[52:53], v[52:53], v[248:249] op_sel:[0,1] op_sel_hi:[1,1]
	v_pk_mul_f32 v[32:33], v[32:33], v[248:249] op_sel:[0,1] op_sel_hi:[1,1]
	v_pk_mul_f32 v[78:79], v[234:235], v[78:79]
	v_pk_mul_f32 v[60:61], v[242:243], v[60:61]
	v_pk_mul_f32 v[78:79], v[78:79], v[248:249] op_sel:[0,1] op_sel_hi:[1,1]
	v_pk_mul_f32 v[60:61], v[60:61], v[248:249] op_sel:[0,1] op_sel_hi:[1,1]
	v_pk_mul_f32 v[178:179], v[70:71], v[254:255] op_sel_hi:[1,0]
	v_pk_mul_f32 v[180:181], v[80:81], v[254:255] op_sel_hi:[1,0]
	v_pk_mul_f32 v[182:183], v[52:53], v[254:255] op_sel_hi:[1,0]
	v_pk_mul_f32 v[184:185], v[78:79], v[254:255] op_sel_hi:[1,0]
	v_exp_f32_e32 v178, v178
	v_exp_f32_e32 v179, v179
	v_exp_f32_e32 v180, v180
	v_exp_f32_e32 v181, v181
	v_exp_f32_e32 v182, v182
	v_exp_f32_e32 v183, v183
	v_exp_f32_e32 v184, v184
	v_exp_f32_e32 v185, v185
	v_add_u32_e32 v196, 0x90, v223
	v_mad_i64_i32 v[194:195], s[20:21], v196, s56, v[192:193]
	v_pk_add_f32 v[178:179], v[178:179], v[254:255] op_sel:[0,1] op_sel_hi:[1,1]
	v_pk_add_f32 v[180:181], v[180:181], v[254:255] op_sel:[0,1] op_sel_hi:[1,1]
	v_pk_add_f32 v[182:183], v[182:183], v[254:255] op_sel:[0,1] op_sel_hi:[1,1]
	v_pk_add_f32 v[184:185], v[184:185], v[254:255] op_sel:[0,1] op_sel_hi:[1,1]
	v_rcp_f32_e32 v178, v178
	v_rcp_f32_e32 v179, v179
	v_rcp_f32_e32 v180, v180
	v_rcp_f32_e32 v181, v181
	v_rcp_f32_e32 v182, v182
	v_rcp_f32_e32 v183, v183
	v_rcp_f32_e32 v184, v184
	v_rcp_f32_e32 v185, v185
	v_lshl_add_u64 v[194:195], v[194:195], 0, v[190:191]
	v_pk_mul_f32 v[178:179], v[70:71], v[178:179]
	v_pk_mul_f32 v[180:181], v[80:81], v[180:181]
	v_pk_mul_f32 v[182:183], v[52:53], v[182:183]
	v_pk_mul_f32 v[184:185], v[78:79], v[184:185]
	v_pk_mul_f32 v[178:179], v[34:35], v[178:179]
	v_pk_mul_f32 v[180:181], v[62:63], v[180:181]
	v_pk_mul_f32 v[182:183], v[32:33], v[182:183]
	v_pk_mul_f32 v[184:185], v[60:61], v[184:185]
	v_cvt_pk_bf16_f32 v198, v178, v179
	v_cvt_pk_bf16_f32 v199, v180, v181
	v_cvt_pk_bf16_f32 v200, v182, v183
	v_cvt_pk_bf16_f32 v201, v184, v185
	global_store_dwordx4 v[194:195], v[198:201], off
	v_pk_mul_f32 v[48:49], v[228:229], v[48:49]
	v_pk_mul_f32 v[30:31], v[236:237], v[30:31]
	v_pk_mul_f32 v[48:49], v[48:49], v[250:251] op_sel_hi:[1,0]
	v_pk_mul_f32 v[30:31], v[30:31], v[250:251] op_sel_hi:[1,0]
	v_pk_mul_f32 v[46:47], v[230:231], v[46:47]
	v_pk_mul_f32 v[58:59], v[238:239], v[58:59]
	v_pk_mul_f32 v[46:47], v[46:47], v[250:251] op_sel_hi:[1,0]
	v_pk_mul_f32 v[58:59], v[58:59], v[250:251] op_sel_hi:[1,0]
	v_pk_mul_f32 v[44:45], v[232:233], v[44:45]
	v_pk_mul_f32 v[28:29], v[240:241], v[28:29]
	v_pk_mul_f32 v[44:45], v[44:45], v[250:251] op_sel_hi:[1,0]
	v_pk_mul_f32 v[28:29], v[28:29], v[250:251] op_sel_hi:[1,0]
	v_pk_mul_f32 v[76:77], v[234:235], v[76:77]
	v_pk_mul_f32 v[56:57], v[242:243], v[56:57]
	v_pk_mul_f32 v[76:77], v[76:77], v[250:251] op_sel_hi:[1,0]
	v_pk_mul_f32 v[56:57], v[56:57], v[250:251] op_sel_hi:[1,0]
	v_pk_mul_f32 v[178:179], v[48:49], v[254:255] op_sel_hi:[1,0]
	v_pk_mul_f32 v[180:181], v[46:47], v[254:255] op_sel_hi:[1,0]
	v_pk_mul_f32 v[182:183], v[44:45], v[254:255] op_sel_hi:[1,0]
	v_pk_mul_f32 v[184:185], v[76:77], v[254:255] op_sel_hi:[1,0]
	v_exp_f32_e32 v178, v178
	v_exp_f32_e32 v179, v179
	v_exp_f32_e32 v180, v180
	v_exp_f32_e32 v181, v181
	v_exp_f32_e32 v182, v182
	v_exp_f32_e32 v183, v183
	v_exp_f32_e32 v184, v184
	v_exp_f32_e32 v185, v185
	v_add_u32_e32 v196, 0xa0, v223
	v_mad_i64_i32 v[194:195], s[20:21], v196, s56, v[192:193]
	v_pk_add_f32 v[178:179], v[178:179], v[254:255] op_sel:[0,1] op_sel_hi:[1,1]
	v_pk_add_f32 v[180:181], v[180:181], v[254:255] op_sel:[0,1] op_sel_hi:[1,1]
	v_pk_add_f32 v[182:183], v[182:183], v[254:255] op_sel:[0,1] op_sel_hi:[1,1]
	v_pk_add_f32 v[184:185], v[184:185], v[254:255] op_sel:[0,1] op_sel_hi:[1,1]
	v_rcp_f32_e32 v178, v178
	v_rcp_f32_e32 v179, v179
	v_rcp_f32_e32 v180, v180
	v_rcp_f32_e32 v181, v181
	v_rcp_f32_e32 v182, v182
	v_rcp_f32_e32 v183, v183
	v_rcp_f32_e32 v184, v184
	v_rcp_f32_e32 v185, v185
	v_lshl_add_u64 v[194:195], v[194:195], 0, v[190:191]
	v_pk_mul_f32 v[178:179], v[48:49], v[178:179]
	v_pk_mul_f32 v[180:181], v[46:47], v[180:181]
	v_pk_mul_f32 v[182:183], v[44:45], v[182:183]
	v_pk_mul_f32 v[184:185], v[76:77], v[184:185]
	v_pk_mul_f32 v[178:179], v[30:31], v[178:179]
	v_pk_mul_f32 v[180:181], v[58:59], v[180:181]
	v_pk_mul_f32 v[182:183], v[28:29], v[182:183]
	v_pk_mul_f32 v[184:185], v[56:57], v[184:185]
	v_cvt_pk_bf16_f32 v186, v178, v179
	v_cvt_pk_bf16_f32 v187, v180, v181
	v_cvt_pk_bf16_f32 v188, v182, v183
	v_cvt_pk_bf16_f32 v189, v184, v185
	global_store_dwordx4 v[194:195], v[186:189], off
	v_pk_mul_f32 v[42:43], v[228:229], v[42:43]
	v_pk_mul_f32 v[26:27], v[236:237], v[26:27]
	v_pk_mul_f32 v[42:43], v[42:43], v[250:251] op_sel:[0,1] op_sel_hi:[1,1]
	v_pk_mul_f32 v[26:27], v[26:27], v[250:251] op_sel:[0,1] op_sel_hi:[1,1]
	v_pk_mul_f32 v[74:75], v[230:231], v[74:75]
	v_pk_mul_f32 v[54:55], v[238:239], v[54:55]
	v_pk_mul_f32 v[74:75], v[74:75], v[250:251] op_sel:[0,1] op_sel_hi:[1,1]
	v_pk_mul_f32 v[54:55], v[54:55], v[250:251] op_sel:[0,1] op_sel_hi:[1,1]
	v_pk_mul_f32 v[40:41], v[232:233], v[40:41]
	v_pk_mul_f32 v[24:25], v[240:241], v[24:25]
	v_pk_mul_f32 v[40:41], v[40:41], v[250:251] op_sel:[0,1] op_sel_hi:[1,1]
	v_pk_mul_f32 v[24:25], v[24:25], v[250:251] op_sel:[0,1] op_sel_hi:[1,1]
	v_pk_mul_f32 v[68:69], v[234:235], v[68:69]
	v_pk_mul_f32 v[50:51], v[242:243], v[50:51]
	v_pk_mul_f32 v[68:69], v[68:69], v[250:251] op_sel:[0,1] op_sel_hi:[1,1]
	v_pk_mul_f32 v[50:51], v[50:51], v[250:251] op_sel:[0,1] op_sel_hi:[1,1]
	v_pk_mul_f32 v[178:179], v[42:43], v[254:255] op_sel_hi:[1,0]
	v_pk_mul_f32 v[180:181], v[74:75], v[254:255] op_sel_hi:[1,0]
	v_pk_mul_f32 v[182:183], v[40:41], v[254:255] op_sel_hi:[1,0]
	v_pk_mul_f32 v[184:185], v[68:69], v[254:255] op_sel_hi:[1,0]
	v_exp_f32_e32 v178, v178
	v_exp_f32_e32 v179, v179
	v_exp_f32_e32 v180, v180
	v_exp_f32_e32 v181, v181
	v_exp_f32_e32 v182, v182
	v_exp_f32_e32 v183, v183
	v_exp_f32_e32 v184, v184
	v_exp_f32_e32 v185, v185
	v_add_u32_e32 v196, 0xb0, v223
	v_mad_i64_i32 v[194:195], s[20:21], v196, s56, v[192:193]
	v_pk_add_f32 v[178:179], v[178:179], v[254:255] op_sel:[0,1] op_sel_hi:[1,1]
	v_pk_add_f32 v[180:181], v[180:181], v[254:255] op_sel:[0,1] op_sel_hi:[1,1]
	v_pk_add_f32 v[182:183], v[182:183], v[254:255] op_sel:[0,1] op_sel_hi:[1,1]
	v_pk_add_f32 v[184:185], v[184:185], v[254:255] op_sel:[0,1] op_sel_hi:[1,1]
	v_rcp_f32_e32 v178, v178
	v_rcp_f32_e32 v179, v179
	v_rcp_f32_e32 v180, v180
	v_rcp_f32_e32 v181, v181
	v_rcp_f32_e32 v182, v182
	v_rcp_f32_e32 v183, v183
	v_rcp_f32_e32 v184, v184
	v_rcp_f32_e32 v185, v185
	v_lshl_add_u64 v[194:195], v[194:195], 0, v[190:191]
	v_pk_mul_f32 v[178:179], v[42:43], v[178:179]
	v_pk_mul_f32 v[180:181], v[74:75], v[180:181]
	v_pk_mul_f32 v[182:183], v[40:41], v[182:183]
	v_pk_mul_f32 v[184:185], v[68:69], v[184:185]
	v_pk_mul_f32 v[178:179], v[26:27], v[178:179]
	v_pk_mul_f32 v[180:181], v[54:55], v[180:181]
	v_pk_mul_f32 v[182:183], v[24:25], v[182:183]
	v_pk_mul_f32 v[184:185], v[50:51], v[184:185]
	v_cvt_pk_bf16_f32 v198, v178, v179
	v_cvt_pk_bf16_f32 v199, v180, v181
	v_cvt_pk_bf16_f32 v200, v182, v183
	v_cvt_pk_bf16_f32 v201, v184, v185
	global_store_dwordx4 v[194:195], v[198:201], off
	s_waitcnt vmcnt(8)
	s_cbranch_vccnz .LBB0_711
	s_barrier
	s_branch .LBB0_711

	.amdhsa_kernel _Z14fwd_megakernel6Params
		.amdhsa_group_segment_fixed_size 0
		.amdhsa_private_segment_fixed_size 0
		.amdhsa_kernarg_size 424
		.amdhsa_user_sgpr_count 2
		.amdhsa_user_sgpr_dispatch_ptr 0
		.amdhsa_user_sgpr_queue_ptr 0
		.amdhsa_user_sgpr_kernarg_segment_ptr 1
		.amdhsa_user_sgpr_dispatch_id 0
		.amdhsa_user_sgpr_kernarg_preload_length 0
		.amdhsa_user_sgpr_kernarg_preload_offset 0
		.amdhsa_user_sgpr_private_segment_size 0
		.amdhsa_uses_dynamic_stack 0
		.amdhsa_enable_private_segment 0
		.amdhsa_system_sgpr_workgroup_id_x 1
		.amdhsa_system_sgpr_workgroup_id_y 0
		.amdhsa_system_sgpr_workgroup_id_z 0
		.amdhsa_system_sgpr_workgroup_info 0
		.amdhsa_system_vgpr_workitem_id 2
		.amdhsa_next_free_vgpr 256
		.amdhsa_next_free_sgpr 102
		.amdhsa_accum_offset 256
		.amdhsa_reserve_vcc 1
		.amdhsa_float_round_mode_32 0
		.amdhsa_float_round_mode_16_64 0
		.amdhsa_float_denorm_mode_32 3
		.amdhsa_float_denorm_mode_16_64 3
		.amdhsa_dx10_clamp 1
		.amdhsa_ieee_mode 1
		.amdhsa_fp16_overflow 0
		.amdhsa_tg_split 0
		.amdhsa_exception_fp_ieee_invalid_op 0
		.amdhsa_exception_fp_denorm_src 0
		.amdhsa_exception_fp_ieee_div_zero 0
		.amdhsa_exception_fp_ieee_overflow 0
		.amdhsa_exception_fp_ieee_underflow 0
		.amdhsa_exception_fp_ieee_inexact 0
		.amdhsa_exception_int_div_zero 0
	.end_amdhsa_kernel

amdhsa.kernels:
  - .agpr_count:     0
    .args:
      - .offset:         0
        .size:           168
        .value_kind:     by_value
      - .offset:         168
        .size:           4
        .value_kind:     hidden_block_count_x
      - .offset:         172
        .size:           4
        .value_kind:     hidden_block_count_y
      - .offset:         176
        .size:           4
        .value_kind:     hidden_block_count_z
      - .offset:         180
        .size:           2
        .value_kind:     hidden_group_size_x
      - .offset:         182
        .size:           2
        .value_kind:     hidden_group_size_y
      - .offset:         184
        .size:           2
        .value_kind:     hidden_group_size_z
      - .offset:         186
        .size:           2
        .value_kind:     hidden_remainder_x
      - .offset:         188
        .size:           2
        .value_kind:     hidden_remainder_y
      - .offset:         190
        .size:           2
        .value_kind:     hidden_remainder_z
      - .offset:         208
        .size:           8
        .value_kind:     hidden_global_offset_x
      - .offset:         216
        .size:           8
        .value_kind:     hidden_global_offset_y
      - .offset:         224
        .size:           8
        .value_kind:     hidden_global_offset_z
      - .offset:         232
        .size:           2
        .value_kind:     hidden_grid_dims
      - .offset:         256
        .size:           8
        .value_kind:     hidden_multigrid_sync_arg
      - .offset:         288
        .size:           4
        .value_kind:     hidden_dynamic_lds_size
    .group_segment_fixed_size: 0
    .kernarg_segment_align: 8
    .kernarg_segment_size: 424
    .language:       OpenCL C
    .language_version:
      - 2
      - 0
    .max_flat_workgroup_size: 512
    .name:           _Z14fwd_megakernel6Params
    .private_segment_fixed_size: 0
    .sgpr_count:     108
    .sgpr_spill_count: 11
    .symbol:         _Z14fwd_megakernel6Params.kd
    .uniform_work_group_size: 1
    .uses_dynamic_stack: false
    .vgpr_count:     256
    .vgpr_spill_count: 0
    .wavefront_size: 64
